# NA item prologue: first key/value tile loads issued together with the Q loads instead of after the Q staging completes
# baseline (speedup 1.0000x reference)
; __device__ __forceinline__ int v_st(int k, int c) { const int kk = (k & ~0xC) | ((k & 4) << 1) | ((k & 8) >> 1); return ((kk >> 3) * 4 + (c >> 5)) * 512 + ((kk & 7) * 32 + (c & 31)) * 2; }
; __device__ __forceinline__ int v_rd_base(int lane) { return ((lane & 3) << 3) | (((lane >> 2) & 3) << 6) | (((lane >> 4) & 1) << 5) | (((lane >> 5) & 1) << 8); }
; #define SLOAD(i, k0) do { sr_[i].vs0 = *reinterpret_cast<const bf16x8*>(&Vh[(long)((k0) + sr) * LDP + sc]); sr_[i].vs1 = *reinterpret_cast<const bf16x8*>(&Vh[(long)((k0) + 32 + sr) * LDP + sc]); \
;     sr_[i].ks0 = *reinterpret_cast<const bf16x8*>(&Kh[(long)((k0) + ksr) * LDP + ksc]); if (DK == 128) sr_[i].ks1 = *reinterpret_cast<const bf16x8*>(&Kh[(long)((k0) + 32 + ksr) * LDP + ksc]); } while (0)
; #define SWAIT() do { if (SD == 1) asm volatile("s_waitcnt vmcnt(0)" ::: "memory"); else if (DK == 128) asm volatile("s_waitcnt vmcnt(4)" ::: "memory"); else asm volatile("s_waitcnt vmcnt(3)" ::: "memory"); } while (0)
; #define HOOK(P0, P1, j) do { if (NA) na_hook(P0, P1, krow0 + (j), q_row, q_col, win_r, win_c, rpb, inv_scale, hi); } while (0)
; template <int DK, bool NA, bool QL, int SD> ...
;     ...
;   const bf16* Qw = Qb + (long)(wid * 32 + r32) * LDP + hi * 8;
; #pragma unroll
;   for (int d0 = 0; d0 < DK / 16; ++d0) { const bf16x8 qv = *reinterpret_cast<const bf16x8*>(Qw + d0 * 16); if (QL) *reinterpret_cast<bf16x8*>(ql + d0 * 1024) = qv; else qr[d0] = qv; }
;   const int sr = tid >> 4, sc = (tid & 15) * 8, vst0 = v_st(sr, sc), vst1 = v_st(32 + sr, sc);
;   const int ksr = DK == 128 ? sr : (tid >> 3), ksc = DK == 128 ? sc : (tid & 7) * 8;
;   const int vb0 = (int)(uintptr_t)V_lds + v_rd_base(lane);
;   struct { bf16x8 vs0, vs1, ks0, ks1; } sr_[SD];
;     ...
;   f32x16 pA0, pA1, pB0, pB1; float mnA, mnB, alA, alB; bf16x8 pa0, pa1, pa2, pa3;
;   constexpr int SE = 0, SO = SD - 1;
;   SLOAD(SE, 0); asm volatile("s_waitcnt vmcnt(0)" ::: "memory"); SWRITE(0, SE); __syncthreads();
;   qkt<DK, QL>(pA0, pA1, K_lds, qr, ql, r32, hi); HOOK(pA0, pA1, 0); partialSM(pA0, pA1, m_reg, mnA, alA, C, thrRaw);
;   SLOAD(SO, KVBLK); if (SD == 2) { if (2 < NT) SLOAD(SE, 2 * KVBLK); }
;   SWAIT(); SWRITE(1, SO); __syncthreads();
.LBB0_382:
	s_or_b64 exec, exec, s[0:1]
	v_mov_b32_e32 v36, v188
	v_readlane_b32 s0, v254, 57
	v_ashrrev_i32_e32 v0, 6, v36
	v_and_b32_e32 v38, 63, v36
	v_lshl_add_u32 v2, v0, 13, s0
	v_readlane_b32 s0, v253, 0
	v_and_b32_e32 v37, 31, v36
	v_lshlrev_b32_e32 v42, 4, v38
	v_readlane_b32 s1, v253, 1
	v_bfe_u32 v34, v36, 5, 1
	v_add_u32_e32 v147, v2, v42
	v_lshl_or_b32 v0, v0, 5, v37
	v_mov_b64_e32 v[2:3], s[0:1]
	s_movk_i32 s0, 0x2800
	v_mad_i64_i32 v[2:3], s[0:1], v0, s0, v[2:3]
	v_lshlrev_b32_e32 v0, 4, v34
	v_lshl_add_u64 v[6:7], v[2:3], 0, v[0:1]
	global_load_dwordx4 v[2:5], v[6:7], off
	global_load_dwordx4 v[44:47], v[6:7], off offset:32
	global_load_dwordx4 v[48:51], v[6:7], off offset:64
	global_load_dwordx4 v[52:55], v[6:7], off offset:96
	global_load_dwordx4 v[56:59], v[6:7], off offset:128
	global_load_dwordx4 v[60:63], v[6:7], off offset:160
	global_load_dwordx4 v[64:67], v[6:7], off offset:192
	global_load_dwordx4 v[68:71], v[6:7], off offset:224
	v_ashrrev_i32_e32 v39, 4, v36
	v_add_u32_e32 v20, 32, v39
	s_movk_i32 s4, 0x1400
	v_readlane_b32 s2, v253, 4
	v_readlane_b32 s3, v253, 5
	v_lshlrev_b32_e32 v35, 8, v37
	v_or_b32_e32 v43, 32, v0
	v_lshlrev_b32_e32 v6, 1, v20
	v_lshlrev_b32_e32 v116, 3, v36
	v_and_b32_e32 v116, 0x78, v116
	v_mad_i64_i32 v[96:97], s[0:1], v39, s4, 0
	v_or_b32_e32 v96, v96, v116
	v_lshlrev_b64 v[96:97], 1, v[96:97]
	v_mad_i64_i32 v[98:99], s[0:1], v20, s4, 0
	v_or_b32_e32 v98, v98, v116
	v_lshlrev_b64 v[98:99], 1, v[98:99]
	v_lshl_add_u64 v[100:101], s[2:3], 0, v[96:97]
	v_lshl_add_u64 v[104:105], s[2:3], 0, v[98:99]
	v_readlane_b32 s0, v253, 2
	v_readlane_b32 s1, v253, 3
	global_load_dwordx4 v[100:103], v[100:101], off
	global_load_dwordx4 v[104:107], v[104:105], off
	s_nop 1
	v_lshl_add_u64 v[108:109], s[0:1], 0, v[96:97]
	v_lshl_add_u64 v[112:113], s[0:1], 0, v[98:99]
	global_load_dwordx4 v[108:111], v[108:109], off
	global_load_dwordx4 v[112:115], v[112:113], off
	s_waitcnt vmcnt(11)
	ds_write_b128 v147, v[2:5]
	s_waitcnt vmcnt(10)
	ds_write_b128 v147, v[44:47] offset:1024
	s_waitcnt vmcnt(9)
	ds_write_b128 v147, v[48:51] offset:2048
	s_waitcnt vmcnt(8)
	ds_write_b128 v147, v[52:55] offset:3072
	s_waitcnt vmcnt(7)
	ds_write_b128 v147, v[56:59] offset:4096
	s_waitcnt vmcnt(6)
	ds_write_b128 v147, v[60:63] offset:5120
	s_waitcnt vmcnt(5)
	ds_write_b128 v147, v[64:67] offset:6144
	s_waitcnt vmcnt(4)
	ds_write_b128 v147, v[68:71] offset:7168
	v_and_b32_e32 v3, 0xfffff0, v39
	v_lshlrev_b32_e32 v4, 1, v39
	v_lshlrev_b32_e32 v2, 3, v36
	v_and_or_b32 v3, v4, 8, v3
	v_and_b32_e32 v40, 0x78, v2
	v_lshrrev_b32_e32 v4, 1, v39
	v_lshrrev_b32_e32 v3, 1, v3
	v_bfe_u32 v2, v2, 5, 2
	v_and_b32_e32 v5, 3, v39
	v_or_b32_e32 v3, v3, v2
	v_and_or_b32 v4, v4, 4, v5
	v_lshlrev_b32_e32 v18, 1, v40
	v_lshlrev_b32_e32 v3, 9, v3
	v_lshlrev_b32_e32 v4, 6, v4
	v_and_b32_e32 v5, 48, v18
	v_or3_b32 v19, v3, v4, v5
	v_and_b32_e32 v3, 0xfffff0, v20
	v_and_or_b32 v3, v6, 8, v3
	v_lshrrev_b32_e32 v3, 1, v3
	v_or_b32_e32 v2, v3, v2
	v_lshlrev_b32_e32 v2, 9, v2
	v_or3_b32 v21, v2, v4, v5
	v_mad_i64_i32 v[2:3], s[0:1], v39, s4, 0
	v_or_b32_e32 v2, v2, v40
	v_lshlrev_b64 v[10:11], 1, v[2:3]
	v_lshl_add_u64 v[2:3], s[2:3], 0, v[10:11]
	v_mad_i64_i32 v[6:7], s[0:1], v20, s4, 0
	v_or_b32_e32 v6, v6, v40
	v_lshlrev_b64 v[14:15], 1, v[6:7]
	v_lshl_add_u64 v[6:7], s[2:3], 0, v[14:15]
	v_readlane_b32 s0, v253, 2
	v_readlane_b32 s1, v253, 3
	v_add_u32_e32 v152, 0, v19
	v_add_u32_e32 v153, 0, v21
	v_lshl_add_u64 v[10:11], s[0:1], 0, v[10:11]
	v_lshl_add_u64 v[14:15], s[0:1], 0, v[14:15]
	v_readlane_b32 s0, v255, 28
	s_waitcnt vmcnt(0)
	v_readlane_b32 s1, v255, 29
	s_waitcnt vmcnt(3)
	ds_write_b128 v152, v[100:103]
	v_lshlrev_b32_e32 v2, 8, v39
	v_and_b32_e32 v3, 0xf0, v36
	v_bitop3_b32 v2, v18, v2, v3 bitop3:0xde
	v_add_u32_e32 v156, 0, v2
	v_lshlrev_b32_e32 v2, 8, v20
	v_bitop3_b32 v2, v18, v2, v3 bitop3:0xde
	v_add_u32_e32 v157, 0, v2
	v_lshlrev_b32_e32 v2, 4, v36
	v_and_b32_e32 v41, 0xf0, v2
	s_waitcnt vmcnt(2)
	ds_write_b128 v153, v[104:107]
	v_bitop3_b32 v6, v0, v35, v41 bitop3:0xde
	v_add_u32_e32 v158, 0, v6
	s_waitcnt vmcnt(1)
	ds_write_b128 v156, v[108:111] offset:32768
	v_bitop3_b32 v43, v43, v35, v41 bitop3:0xde
	s_waitcnt vmcnt(0)
	ds_write_b128 v157, v[112:115] offset:32768
	s_waitcnt lgkmcnt(0)
	s_barrier
; __device__ __forceinline__ int crow(int r, int hi) { return (r & 3) + 8 * (r >> 2) + 4 * hi; }
; template <int DK, bool QL>
; __device__ __forceinline__ void qkt(f32x16& p0, f32x16& p1, const bf16* Ks, const bf16x8* qr, const char* ql, int r32, int hi) {
;   p0 = f32x16{}; p1 = f32x16{};
; #pragma unroll
;   for (int d0 = 0; d0 < DK / 16; ++d0) { int cb = (d0 * 16 + hi * 8) * 2;
;     const bf16x8 qv = QL ? *reinterpret_cast<const bf16x8*>(ql + d0 * 1024) : qr[d0];
;     bf16x8 b0 = *reinterpret_cast<const bf16x8*>((const char*)Ks + kswz<DK>(r32, cb));
;     bf16x8 b1 = *reinterpret_cast<const bf16x8*>((const char*)Ks + kswz<DK>(32 + r32, cb));
;     p0 = __builtin_amdgcn_mfma_f32_32x32x16_bf16(b0, qv, p0, 0, 0, 0);
;     p1 = __builtin_amdgcn_mfma_f32_32x32x16_bf16(b1, qv, p1, 0, 0, 0); }
; }
; __device__ __forceinline__ void na_hook(f32x16& p0, f32x16& p1, int kr, int q_row, int q_col, int win_r, int win_c, const float* rpb, float inv_scale, int hi) {
;   const bool rowok = (kr >= win_r) && (kr < win_r + 8);
;   int ir = kr - q_row + 7; ir = ir < 0 ? 0 : (ir > 14 ? 14 : ir);
;   const float* rp = rpb + ir * 31;
; #pragma unroll
;   for (int r = 0; r < 16; ++r) {
;     const int kc = crow(r, hi);
;     { const bool ok = rowok && kc >= win_c && kc < win_c + 16; int ic = kc - q_col + 15; ic = ic < 0 ? 0 : (ic > 30 ? 30 : ic);
;       p0[r] = ok ? fmaf(rp[ic], inv_scale, p0[r]) : -1e30f; }
;     { const int kc2 = kc + 32; const bool ok = rowok && kc2 >= win_c && kc2 < win_c + 16; int ic = kc2 - q_col + 15; ic = ic < 0 ? 0 : (ic > 30 ? 30 : ic);
;       p1[r] = ok ? fmaf(rp[ic], inv_scale, p1[r]) : -1e30f; }
;   }
; }
	ds_read_b128 v[2:5], v147
	ds_read_b128 v[6:9], v158 offset:32768
	ds_read_b128 v[10:13], v158 offset:40960
	s_waitcnt lgkmcnt(1)
	v_mfma_f32_32x32x16_bf16 v[18:33], v[6:9], v[2:5], 0
	v_add_u32_e32 v159, 0, v43
	ds_read_b128 v[44:47], v147 offset:1024
	ds_read_b128 v[48:51], v159 offset:32768
	ds_read_b128 v[52:55], v159 offset:40960
	v_or_b32_e32 v43, 64, v0
	v_bitop3_b32 v43, v43, v35, v41 bitop3:0xde
	v_add_u32_e32 v160, 0, v43
	v_or_b32_e32 v43, 0x60, v0
	s_waitcnt lgkmcnt(3)
	v_mfma_f32_32x32x16_bf16 v[2:17], v[10:13], v[2:5], 0
	v_bitop3_b32 v43, v43, v35, v41 bitop3:0xde
	v_add_u32_e32 v161, 0, v43
	v_or_b32_e32 v43, 0x80, v0
	v_bitop3_b32 v43, v43, v35, v41 bitop3:0xde
	v_add_u32_e32 v176, 0, v43
	v_or_b32_e32 v43, 0xa0, v0
	v_bitop3_b32 v43, v43, v35, v41 bitop3:0xde
	s_waitcnt lgkmcnt(1)
	v_mfma_f32_32x32x16_bf16 v[18:33], v[48:51], v[44:47], v[18:33]
	v_add_u32_e32 v177, 0, v43
	v_or_b32_e32 v43, 0xc0, v0
	v_bitop3_b32 v43, v43, v35, v41 bitop3:0xde
	v_add_u32_e32 v207, 0, v43
	v_or_b32_e32 v0, 0xe0, v0
	v_bitop3_b32 v0, v0, v35, v41 bitop3:0xde
	v_add_u32_e32 v208, 0, v0
	s_waitcnt lgkmcnt(0)
	v_mfma_f32_32x32x16_bf16 v[2:17], v[52:55], v[44:47], v[2:17]
	ds_read_b128 v[44:47], v147 offset:2048
	ds_read_b128 v[48:51], v160 offset:32768
	ds_read_b128 v[52:55], v160 offset:40960
	v_lshlrev_b32_e32 v0, 2, v34
	v_cmp_lt_u32_e64 s[2:3], v0, v182
	v_mov_b32_e32 v34, 0xf149f2ca
	v_sub_u32_e32 v41, v0, v181
	v_writelane_b32 v255, s2, 50
	s_waitcnt lgkmcnt(1)
	v_mfma_f32_32x32x16_bf16 v[18:33], v[48:51], v[44:47], v[18:33]
	v_mov_b32_e32 v43, 0xf149f2ca
	v_writelane_b32 v255, s3, 51
	s_nor_b64 s[2:3], s[0:1], s[2:3]
	s_waitcnt lgkmcnt(0)
	v_mfma_f32_32x32x16_bf16 v[2:17], v[52:55], v[44:47], v[2:17]
	ds_read_b128 v[44:47], v147 offset:3072
	ds_read_b128 v[48:51], v161 offset:32768
	ds_read_b128 v[52:55], v161 offset:40960
	s_waitcnt lgkmcnt(1)
	v_mfma_f32_32x32x16_bf16 v[18:33], v[48:51], v[44:47], v[18:33]
	s_waitcnt lgkmcnt(0)
	v_mfma_f32_32x32x16_bf16 v[2:17], v[52:55], v[44:47], v[2:17]
	ds_read_b128 v[44:47], v147 offset:4096
	ds_read_b128 v[48:51], v176 offset:32768
	ds_read_b128 v[52:55], v176 offset:40960
	s_waitcnt lgkmcnt(1)
	v_mfma_f32_32x32x16_bf16 v[18:33], v[48:51], v[44:47], v[18:33]
	s_waitcnt lgkmcnt(0)
	v_mfma_f32_32x32x16_bf16 v[2:17], v[52:55], v[44:47], v[2:17]
	ds_read_b128 v[44:47], v147 offset:5120
	ds_read_b128 v[48:51], v177 offset:32768
	ds_read_b128 v[52:55], v177 offset:40960
	s_waitcnt lgkmcnt(1)
	v_mfma_f32_32x32x16_bf16 v[18:33], v[48:51], v[44:47], v[18:33]
	s_waitcnt lgkmcnt(0)
	v_mfma_f32_32x32x16_bf16 v[2:17], v[52:55], v[44:47], v[2:17]
	ds_read_b128 v[44:47], v147 offset:6144
	ds_read_b128 v[48:51], v207 offset:32768
	ds_read_b128 v[52:55], v207 offset:40960
	s_waitcnt lgkmcnt(1)
	v_mfma_f32_32x32x16_bf16 v[18:33], v[48:51], v[44:47], v[18:33]
	s_waitcnt lgkmcnt(0)
	v_mfma_f32_32x32x16_bf16 v[2:17], v[52:55], v[44:47], v[2:17]
	ds_read_b128 v[44:47], v147 offset:7168
	ds_read_b128 v[48:51], v208 offset:32768
	ds_read_b128 v[52:55], v208 offset:40960
	s_waitcnt lgkmcnt(1)
	v_mfma_f32_32x32x16_bf16 v[18:33], v[48:51], v[44:47], v[18:33]
	s_waitcnt lgkmcnt(0)
	v_mfma_f32_32x32x16_bf16 v[2:17], v[52:55], v[44:47], v[2:17]
	s_and_saveexec_b64 s[0:1], s[2:3]
	s_cbranch_execz .LBB0_384
	v_sub_u32_e32 v35, v0, v181
	v_max_i32_e32 v35, -15, v35
	v_lshl_add_u32 v35, v35, 2, v183
	ds_read_b32 v35, v35 offset:928
	s_waitcnt lgkmcnt(0)
	s_nop 2
	v_fmamk_f32 v43, v35, 0x413504f3, v18
